# P0 rows loop: wave-wide sum of squares via four DPP adds and two permlane16/32 swaps instead of six ds_bpermute round trips per row
# speedup vs baseline: 1.0010x; 1.0010x over previous
.LBB0_110:
	global_load_dwordx4 v[28:31], v[214:215], off
	global_load_dwordx4 v[32:35], v[214:215], off offset:1024
	global_load_dwordx4 v[36:39], v[214:215], off offset:2048
	global_load_dwordx4 v[40:43], v[214:215], off offset:3072
	s_waitcnt vmcnt(5) lgkmcnt(0)
	v_mov_b64_e32 v[12:13], v[120:121]
	v_mov_b64_e32 v[14:15], v[122:123]
	v_mov_b64_e32 v[8:9], v[124:125]
	v_mov_b64_e32 v[10:11], v[126:127]
	v_mov_b64_e32 v[4:5], v[144:145]
	v_mov_b64_e32 v[6:7], v[146:147]
	v_mov_b64_e32 v[0:1], v[148:149]
	v_mov_b64_e32 v[2:3], v[150:151]
	v_mul_f32_e32 v16, v13, v13
	v_mul_f32_e32 v17, v15, v15
	v_mul_f32_e32 v18, v9, v9
	v_mul_f32_e32 v19, v11, v11
	v_mul_f32_e32 v20, v5, v5
	v_mul_f32_e32 v21, v7, v7
	v_fmac_f32_e32 v16, v12, v12
	v_fmac_f32_e32 v17, v14, v14
	v_fmac_f32_e32 v18, v8, v8
	v_fmac_f32_e32 v19, v10, v10
	v_mul_f32_e32 v22, v1, v1
	v_mul_f32_e32 v23, v3, v3
	v_fmac_f32_e32 v20, v4, v4
	v_fmac_f32_e32 v21, v6, v6
	v_add_f32_e32 v16, v16, v17
	v_add_f32_e32 v17, v18, v19
	v_fmac_f32_e32 v22, v0, v0
	v_fmac_f32_e32 v23, v2, v2
	v_add_f32_e32 v18, v20, v21
	v_add_f32_e32 v16, v16, v17
	v_add_f32_e32 v16, v16, v18
	v_add_f32_e32 v17, v22, v23
	v_add_f32_e32 v16, v16, v17
	s_nop 1
	v_add_f32_dpp v16, v16, v16 quad_perm:[1,0,3,2] row_mask:0xf bank_mask:0xf
	s_nop 1
	v_add_f32_dpp v16, v16, v16 quad_perm:[2,3,0,1] row_mask:0xf bank_mask:0xf
	s_nop 1
	v_add_f32_dpp v16, v16, v16 row_half_mirror row_mask:0xf bank_mask:0xf
	s_nop 1
	v_add_f32_dpp v16, v16, v16 row_mirror row_mask:0xf bank_mask:0xf
	v_mov_b32_e32 v17, v16
	s_nop 1
	v_permlane16_swap_b32_e32 v16, v17
	v_add_f32_e32 v16, v16, v17
	v_mov_b32_e32 v17, v16
	s_nop 1
	v_permlane32_swap_b32_e32 v16, v17
	v_add_f32_e32 v16, v16, v17
	s_and_saveexec_b64 s[18:19], s[6:7]
	s_cbranch_execz .LBB0_112
	s_add_u32 s52, s40, s48
	s_addc_u32 s53, s41, s49
	global_store_dword v213, v16, s[52:53]
